# mLSTM: conflict-free LDS layout for Qs/Ks/Cs fragment reads (fixed 16B-chunk permutation within rows)
# speedup vs baseline: 1.0353x; 1.0353x over previous
; __device__ __forceinline__ void mlstm_item(const Args& a, LAS unsigned char* L, bool sample, int b, int hh, int sl, bool dry = false) {
;     ...
;     for (int c = 0; c < nchunks; ++c) {
; #pragma unroll
;         for (int i = 0; i < 2; ++i) { *(LAS u32x4*)(L + L_QS + (prow + 16 * i) * 528 + pcc * 16) = qreg[i]; *(LAS u32x4*)(L + L_KS + (prow + 16 * i) * 528 + pcc * 16) = kreg[i]; }
;         if (tid < 256) {
;             const float wL0 = GWL[c * 32 + 2 * sp], wL1 = GWL[c * 32 + 2 * sp + 1];
;             const unsigned r0w[2] = {vreg0.x, vreg0.y}, r1w[2] = {vreg1.x, vreg1.y};
; #pragma unroll
;             for (int i = 0; i < 4; ++i) { const unsigned e0 = (i & 1) ? (r0w[i >> 1] >> 16) : (r0w[i >> 1] & 0xffffu), e1 = (i & 1) ? (r1w[i >> 1] >> 16) : (r1w[i >> 1] & 0xffffu);
;                 *(LAS unsigned*)(L + L_VT + (vq * 4 + i) * 80 + sp * 4) = e0 | (e1 << 16);
;                 *(LAS unsigned*)(L + L_VTW + (vq * 4 + i) * 80 + sp * 4) = pk2(bf2f(e0) * wL0, bf2f(e1) * wL1); }
;             if (tid < 16) *(LAS unsigned*)(L + L_VTW + 64 * 80 + sp * 4) = pk2(wL0, wL1);
;         }
;         if (c + 1 < nchunks) PREFETCH(c + 1);
;         LDS_BARRIER();
;         const float dL = GDL[c], m0c = GM0[c];
;         if (wave < 4) {
;             const int st = wave >> 1, tt = wave & 1, t = tt * 16 + lr;
;             f32x4 s = (f32x4){0.f, 0.f, 0.f, 0.f};
;             if (!(st == 1 && tt == 0)) {
;                 bf16x8 Af[8], Bf[8];
; #pragma unroll
;                 for (int kk = 0; kk < 8; ++kk) { Af[kk] = *(const LAS bf16x8*)(L + L_KS + (st * 16 + lr) * 528 + kk * 64 + g * 16); Bf[kk] = *(const LAS bf16x8*)(L + L_QS + t * 528 + kk * 64 + g * 16); }
;                 __builtin_amdgcn_sched_barrier(0);
; #pragma unroll
;                 for (int kk = 0; kk < 8; ++kk) s = MFMA16(Af[kk], Bf[kk], s);
;             }
;             const float fmt = GFM[c * 32 + t];
;             const f32x4 as4 = *(const LAS f32x4*)(L + L_GAA + (c * 32 + st * 16 + g * 4) * 4);
;             float val[4];
; #pragma unroll
;             for (int j = 0; j < 4; ++j) { const int si = st * 16 + g * 4 + j; const float e = __expf(fminf(fmt + as4[j], 0.f)); val[j] = (si <= t) ? s[j] * e : 0.f; }
;             *(LAS u32x2*)(L + L_SS + t * 80 + (st * 16 + g * 4) * 2) = (u32x2){pk2(val[0], val[1]), pk2(val[2], val[3])};
;             float rsum = (val[0] + val[1]) + (val[2] + val[3]);
.LBB0_659:
	s_or_b64 exec, exec, s[4:5]
	s_lshr_b32 s4, s92, 3
	s_and_b32 s59, s4, 3
	s_lshl_b32 s97, s94, 6
	s_cmp_gt_i32 s55, 3
	s_cselect_b64 s[68:69], -1, 0
	s_add_i32 s4, s55, -4
	s_lshr_b32 s6, s4, 1
	v_and_b32_e32 v99, 48, v83
	v_bfe_u32 v222, v83, 5, 1
	v_lshlrev_b32_e32 v222, 4, v222
	v_bfe_u32 v223, v83, 4, 1
	v_lshl_or_b32 v222, v223, 8, v222
	v_bfe_u32 v223, v83, 5, 1
	v_mul_u32_u24_e32 v223, 0xf0, v223
	v_lshrrev_b32_e32 v226, 1, v83
	v_and_b32_e32 v226, 0xffffffe0, v226
	v_sub_u32_e32 v223, v223, v226
	v_bfe_u32 v224, v83, 2, 3
	v_lshlrev_b32_e32 v224, 5, v224
	v_bfe_u32 v227, v83, 1, 1
	v_lshl_or_b32 v224, v227, 4, v224
	v_and_b32_e32 v228, 1, v83
	v_lshl_or_b32 v224, v228, 8, v224
	v_lshlrev_b32_e32 v225, 8, v227
	v_lshl_or_b32 v225, v228, 3, v225
	v_add_u32_e32 v225, v225, v226
	s_lshl_b32 s4, s55, 4
	v_lshl_add_u32 v103, s6, 7, v222
	s_lshl_b32 s6, s6, 5
	v_lshlrev_b32_e32 v66, 2, v84
	s_and_b32 s17, s4, 16
	s_add_i32 s6, s6, 64
	s_ashr_i32 s70, s12, 7
	s_bfe_u32 s71, s12, 0x10006
	v_lshl_add_u32 v21, v24, 4, 0
	v_add_u32_e32 v106, 0, v66
	v_or_b32_e32 v88, s17, v84
	v_mul_u32_u24_e32 v24, 0x20c, v84
	s_mov_b32 s4, 0xc000
	s_cmp_lg_u32 s70, 1
	v_add3_u32 v105, v106, v24, s4
	v_or_b32_e32 v24, s6, v88
	s_cselect_b64 s[6:7], -1, 0
	s_bitcmp1_b32 s12, 6
	s_cselect_b64 s[8:9], -1, 0
	s_or_b64 s[64:65], s[6:7], s[8:9]
	s_lshl_b32 s6, s70, 4
	v_lshlrev_b32_e32 v102, 2, v24
	v_or_b32_e32 v24, s6, v84
	v_mul_lo_u32 v24, v24, s83
	v_lshlrev_b32_e32 v68, 2, v23
	v_add_u32_e32 v101, 0, v24
	v_or_b32_e32 v98, s6, v68
	s_and_b32 s6, s12, 0xffffff80
	v_lshrrev_b32_e32 v24, 2, v84
	s_add_i32 s86, s35, s6
	v_or_b32_e32 v24, v26, v24
	s_ashr_i32 s6, s12, 3
	s_lshl_b32 s16, s58, 9
	v_mad_u32_u24 v28, v24, s83, 0
	v_lshlrev_b32_e32 v24, 3, v83
	s_and_b32 s56, s6, -16
	s_add_i32 s42, s42, s16
	v_and_or_b32 v29, v24, 24, s13
	v_or_b32_e32 v24, s56, v84
	s_and_b32 s16, s42, 0xfffff800
	v_mul_lo_u32 v26, v24, s82
	s_or_b32 s17, s16, s17
	v_add_u32_e32 v70, 0, v26
	s_movk_i32 s6, 0x1c0
	v_or_b32_e32 v109, s17, v84
	s_lshl_b32 s17, s70, 6
	v_cmp_gt_u32_e64 s[4:5], 16, v27
	v_lshl_or_b32 v96, s71, 4, v84
	v_mad_u64_u32 v[26:27], s[6:7], v24, s6, v[70:71]
	v_or_b32_e32 v24, 2, v98
	s_add_i32 s17, s17, 0x18500
	v_cmp_gt_i32_e64 s[10:11], v24, v96
	v_or_b32_e32 v24, 3, v98
	v_lshl_or_b32 v111, v23, 4, s17
	v_mul_hi_u32_u24_e32 v23, 0x7000, v84
	s_mul_hi_i32 s42, s16, 0x3800
	v_mul_lo_u32 v108, v25, s87
	v_cmp_gt_i32_e64 s[6:7], v24, v96
	v_mul_u32_u24_e32 v24, 0x7000, v84
	s_mul_i32 s58, s16, 0x3800
	v_or_b32_e32 v25, s42, v23
	s_lshl_b32 s42, s92, 4
	v_or_b32_e32 v23, s58, v24
	s_and_b32 s42, s42, 0x600
	v_or_b32_e32 v23, s42, v23
	s_ashr_i32 s17, s16, 31
	v_lshl_or_b32 v24, s59, 7, v23
	v_mul_lo_u32 v27, v16, s83
	v_lshl_add_u64 v[18:19], v[18:19], 1, v[24:25]
	v_lshl_add_u64 v[16:17], v[16:17], 0, s[16:17]
	s_waitcnt lgkmcnt(0)
	s_barrier
	v_mad_u32_u24 v104, v88, s83, 0
	v_lshl_add_u64 v[72:73], s[28:29], 0, v[18:19]
	v_mad_u64_u32 v[18:19], s[16:17], v16, s84, 0
	v_mul_u32_u24_e32 v20, 0x210, v84
	v_lshlrev_b32_e32 v107, 3, v84
	v_mad_u32_u24 v100, v96, s83, 0
	v_add_u32_e32 v30, 0, v99
	v_mad_i32_i24 v31, v88, s33, v104
	v_mul_u32_u24_e32 v32, 0x50, v84
	v_mad_i32_i24 v17, v17, s84, v19
	v_or3_b32 v16, v18, s42, v60
	v_mov_b32_e32 v36, 0
	v_cmp_gt_i32_e64 s[14:15], 16, v83
	v_mad_i32_i24 v93, v96, s33, v100
	v_lshlrev_b32_e32 v94, 1, v98
	v_lshlrev_b32_e32 v92, 2, v96
	v_lshl_add_u32 v89, v88, 2, s35
	s_ashr_i32 s57, s56, 31
	v_cmp_gt_i32_e64 s[12:13], v98, v96
	v_cmp_lt_i32_e64 s[8:9], v98, v96
	v_lshl_or_b32 v110, s71, 6, v66
	v_lshl_add_u64 v[74:75], s[28:29], 0, v[16:17]
	s_mov_b32 s16, 0
	s_mov_b64 s[70:71], 0
	s_lshl_b32 s58, s97, 1
	v_lshlrev_b32_e32 v60, 1, v68
	v_add_u32_e32 v112, v224, v27
	v_add_u32_e32 v97, v28, v225
	v_add_u32_e32 v95, v30, v32
	v_add_u32_e32 v91, v31, v99
	v_add_u32_e32 v90, v26, v222
	v_add_u32_e32 v113, v22, v20
	v_add_u32_e32 v113, v113, v223
	v_add_u32_e32 v86, v86, v223
	v_add_u32_e32 v85, v85, v223
	v_add_u32_e32 v67, v67, v223
	v_mov_b32_e32 v114, v107
	v_mov_b32_e32 v37, v36
	v_mov_b32_e32 v38, v36
	v_mov_b32_e32 v39, v36
	v_mov_b32_e32 v52, v36
	v_mov_b32_e32 v53, v36
	v_mov_b32_e32 v54, v36
	v_mov_b32_e32 v55, v36
	v_mov_b32_e32 v48, v36
	v_mov_b32_e32 v49, v36
	v_mov_b32_e32 v50, v36
	v_mov_b32_e32 v51, v36
	v_mov_b32_e32 v44, v36
	v_mov_b32_e32 v45, v36
	v_mov_b32_e32 v46, v36
	v_mov_b32_e32 v47, v36
	v_mov_b32_e32 v40, v36
	v_mov_b32_e32 v41, v36
	v_mov_b32_e32 v42, v36
	v_mov_b32_e32 v43, v36
	v_mov_b32_e32 v32, v36
	v_mov_b32_e32 v33, v36
	v_mov_b32_e32 v34, v36
	v_mov_b32_e32 v35, v36
	v_mov_b32_e32 v28, v36
	v_mov_b32_e32 v29, v36
	v_mov_b32_e32 v30, v36
	v_mov_b32_e32 v31, v36
	v_mov_b32_e32 v24, v36
	v_mov_b32_e32 v25, v36
	v_mov_b32_e32 v26, v36
	v_mov_b32_e32 v27, v36
	v_mov_b32_e32 v20, v36
	v_mov_b32_e32 v21, v36
	v_mov_b32_e32 v22, v36
	v_mov_b32_e32 v23, v36
	v_mov_b32_e32 v16, v36
	v_mov_b32_e32 v17, v36
	v_mov_b32_e32 v18, v36
	v_mov_b32_e32 v19, v36
	s_branch .LBB0_662

; #define LAS __attribute__((address_space(3)))
; __device__ __forceinline__ void mlstm_item(const Args& a, LAS unsigned char* L, bool sample, int b, int hh, int sl, bool dry = false) {
;     ...
;             v4i16_t tl[2], th[2]; bf16x8 Bv[5];
; #pragma unroll
;             for (int kti = 0; kti < 2; ++kti) { const int kt = 2 * wave + kti;
;                 tl[kti] = __builtin_amdgcn_ds_read_tr16_b64_v4i16((LAS v4i16_t*)(L + L_KS + (g * 8 + (lr >> 2)) * 528 + (kt * 16 + 4 * (lr & 3)) * 2));
;                 th[kti] = __builtin_amdgcn_ds_read_tr16_b64_v4i16((LAS v4i16_t*)(L + L_KS + (g * 8 + 4 + (lr >> 2)) * 528 + (kt * 16 + 4 * (lr & 3)) * 2)); }
; #pragma unroll
;             for (int vt = 0; vt < 5; ++vt) Bv[vt] = *(const LAS bf16x8*)(L + L_VTW + (vt * 16 + lr) * 80 + g * 16);
; #pragma unroll
;             for (int kti = 0; kti < 2; ++kti) { const bf16x8 A = (bf16x8){tl[kti][0], tl[kti][1], tl[kti][2], tl[kti][3], th[kti][0], th[kti][1], th[kti][2], th[kti][3]};
; #pragma unroll
;                 for (int vt = 0; vt < 5; ++vt) Cacc[kti][vt] = MFMA16(A, Bv[vt], Cacc[kti][vt] * dL); }
;         }
;         LDS_BARRIER();
;         {
;             const int tt = wave & 1, vt = wave >> 1, t = tt * 16 + lr;
;             const bf16x8 Bs = *(const LAS bf16x8*)(L + L_SS + t * 80 + g * 16);
;             const f32x4 z4 = (f32x4){0.f, 0.f, 0.f, 0.f};
;             const bf16x8 Av = *(const LAS bf16x8*)(L + L_VT + (vt * 16 + lr) * 80 + g * 16);
;             bf16x8 Af[8], Bf[8];
; #pragma unroll
;             for (int kk = 0; kk < 8; ++kk) { Af[kk] = *(const LAS bf16x8*)(L + L_CS + (vt * 16 + lr) * 528 + kk * 64 + g * 16); Bf[kk] = *(const LAS bf16x8*)(L + L_QS + t * 528 + kk * 64 + g * 16); }
;             __builtin_amdgcn_sched_barrier(0);
;             f32x4 sM = MFMA16(Av, Bs, z4);
;             f32x4 cM = z4;
; #pragma unroll
;             for (int kk = 0; kk < 8; ++kk) cM = MFMA16(Af[kk], Bf[kk], cM);
;             const float d0 = __expf(m0c + GFM[c * 32 + t]), en = GEN[c * 32 + t];
;             const LAS float* NQ = (const LAS float*)(L + L_NQ);
;             const float nq = (NQ[t] + NQ[32 + t]) + d0 * (NQ[64 + t] + NQ[96 + t]);
;             const float inv = __builtin_amdgcn_rcpf(fmaxf(fabsf(nq), en));
;             float hv[4];
; #pragma unroll
;             for (int j = 0; j < 4; ++j) hv[j] = (sM[j] + d0 * cM[j]) * inv;
.LBB0_661:
	ds_read_b64_tr_b16 v[58:59], v97 offset:19008
	s_waitcnt lgkmcnt(1)
	ds_read_b64_tr_b16 v[56:57], v97 offset:16896
	ds_read_b64_tr_b16 v[116:117], v97 offset:16912
	ds_read_b64_tr_b16 v[118:119], v97 offset:19024
	ds_read_b128 v[120:123], v95 offset:40192
	ds_read_b128 v[124:127], v95 offset:41472
	ds_read_b128 v[128:131], v95 offset:42752
	ds_read_b128 v[132:135], v95 offset:44032
	ds_read_b128 v[136:139], v95 offset:45312
	v_pk_mul_f32 v[38:39], v[38:39], v[76:77] op_sel_hi:[1,0]
	v_pk_mul_f32 v[36:37], v[36:37], v[76:77] op_sel_hi:[1,0]
	v_pk_mul_f32 v[54:55], v[54:55], v[76:77] op_sel_hi:[1,0]
	v_pk_mul_f32 v[52:53], v[52:53], v[76:77] op_sel_hi:[1,0]
	v_pk_mul_f32 v[50:51], v[50:51], v[76:77] op_sel_hi:[1,0]
	v_pk_mul_f32 v[48:49], v[48:49], v[76:77] op_sel_hi:[1,0]
	v_pk_mul_f32 v[46:47], v[46:47], v[76:77] op_sel_hi:[1,0]
	v_pk_mul_f32 v[44:45], v[44:45], v[76:77] op_sel_hi:[1,0]
	v_pk_mul_f32 v[42:43], v[42:43], v[76:77] op_sel_hi:[1,0]
	v_pk_mul_f32 v[40:41], v[40:41], v[76:77] op_sel_hi:[1,0]
	s_waitcnt lgkmcnt(4)
	v_mfma_f32_16x16x32_bf16 v[36:39], v[56:59], v[120:123], v[36:39]
	v_mul_f32_e64 v34, v34, v76
	v_mul_f32_e64 v35, v35, v76
	v_pk_mul_f32 v[32:33], v[32:33], v[76:77] op_sel_hi:[1,0]
	v_pk_mul_f32 v[30:31], v[30:31], v[76:77] op_sel_hi:[1,0]
	s_waitcnt lgkmcnt(3)
	v_mfma_f32_16x16x32_bf16 v[52:55], v[56:59], v[124:127], v[52:55]
	v_mul_f32_e64 v28, v28, v76
	v_mul_f32_e64 v29, v29, v76
	v_pk_mul_f32 v[26:27], v[26:27], v[76:77] op_sel_hi:[1,0]
	v_pk_mul_f32 v[24:25], v[24:25], v[76:77] op_sel_hi:[1,0]
	s_waitcnt lgkmcnt(2)
	v_mfma_f32_16x16x32_bf16 v[48:51], v[56:59], v[128:131], v[48:51]
	v_mul_f32_e64 v22, v22, v76
	v_mul_f32_e64 v23, v23, v76
	v_pk_mul_f32 v[20:21], v[20:21], v[76:77] op_sel_hi:[1,0]
	v_pk_mul_f32 v[18:19], v[18:19], v[76:77] op_sel_hi:[1,0]
	s_waitcnt lgkmcnt(1)
	v_mfma_f32_16x16x32_bf16 v[44:47], v[56:59], v[132:135], v[44:47]
	v_mul_f32_e64 v16, v16, v76
	v_mul_f32_e64 v17, v17, v76
	s_waitcnt lgkmcnt(0)
	s_barrier
	s_waitcnt lgkmcnt(0)
	v_mfma_f32_16x16x32_bf16 v[40:43], v[56:59], v[136:139], v[40:43]
	v_add_u32_e32 v58, v70, v99
	v_add_u32_e32 v57, v104, v222
	v_mfma_f32_16x16x32_bf16 v[32:35], v[116:119], v[120:123], v[32:35]
	v_mfma_f32_16x16x32_bf16 v[28:31], v[116:119], v[124:127], v[28:31]
	v_mfma_f32_16x16x32_bf16 v[24:27], v[116:119], v[128:131], v[24:27]
	v_mfma_f32_16x16x32_bf16 v[20:23], v[116:119], v[132:135], v[20:23]
	v_mfma_f32_16x16x32_bf16 v[16:19], v[116:119], v[136:139], v[16:19]
	ds_read_b128 v[116:119], v91 offset:46592
	ds_read_b128 v[120:123], v58 offset:33792
	ds_read_b128 v[124:127], v90 offset:49152
	ds_read_b128 v[128:131], v57
	ds_read_b128 v[132:135], v90 offset:49184
	ds_read_b128 v[136:139], v57 offset:32
	ds_read_b128 v[140:143], v90 offset:49216
	ds_read_b128 v[144:147], v57 offset:64
	ds_read_b128 v[148:151], v90 offset:49248
	ds_read_b128 v[152:155], v57 offset:96
	ds_read_b128 v[156:159], v90 offset:49280
	ds_read_b128 v[160:163], v57 offset:128
	ds_read_b128 v[164:167], v90 offset:49312
	ds_read_b128 v[168:171], v57 offset:160
	ds_read_b128 v[172:175], v90 offset:49344
	ds_read_b128 v[176:179], v57 offset:192
	ds_read_b128 v[182:185], v90 offset:49376
	ds_read_b128 v[186:189], v57 offset:224
	s_waitcnt lgkmcnt(14)
	v_mfma_f32_16x16x32_bf16 v[124:127], v[124:127], v[128:131], 0
	v_add_u32_e32 v56, 0, v110
	v_add_u32_e32 v59, 0x16500, v56
	ds_read_b32 v59, v59
	s_waitcnt lgkmcnt(13)
	v_mfma_f32_16x16x32_bf16 v[124:127], v[132:135], v[136:139], v[124:127]
	v_add_u32_e32 v56, 0x1a500, v56
	ds_read2_b32 v[128:129], v89 offset1:32
	ds_read_b32 v56, v56
	ds_read2_b32 v[130:131], v89 offset0:64 offset1:96
	s_waitcnt lgkmcnt(14)
	v_mfma_f32_16x16x32_bf16 v[124:127], v[140:143], v[144:147], v[124:127]
	s_waitcnt lgkmcnt(3)
	v_add_f32_e32 v59, v115, v59
	v_mul_f32_e32 v59, 0x3fb8aa3b, v59
	v_exp_f32_e32 v59, v59
	v_mfma_f32_16x16x32_bf16 v[124:127], v[148:151], v[152:155], v[124:127]
	s_waitcnt lgkmcnt(2)
	v_mov_b32_e32 v132, v128
	s_waitcnt lgkmcnt(0)
	v_mov_b32_e32 v133, v130
	v_mov_b32_e32 v130, v129
	v_mfma_f32_16x16x32_bf16 v[124:127], v[156:159], v[160:163], v[124:127]
	v_add_f32_e64 v128, v132, v130
	v_add_f32_e64 v129, v133, v131
	v_max_f32_e32 v56, v56, v56
	v_fmac_f32_e32 v128, v59, v129
	v_mfma_f32_16x16x32_bf16 v[124:127], v[164:167], v[168:171], v[124:127]
	v_max_f32_e64 v56, |v128|, v56
	v_rcp_f32_e32 v56, v56
	s_lshl_b32 s42, s53, 1
	v_mfma_f32_16x16x32_bf16 v[124:127], v[172:175], v[176:179], v[124:127]
	s_mov_b32 s59, s43
	s_add_i32 s16, s16, 4
	s_add_u32 s70, s70, 0x70000
	v_mfma_f32_16x16x32_bf16 v[124:127], v[182:185], v[186:189], v[124:127]
	s_addc_u32 s71, s71, 0
	v_add_u32_e32 v114, 0x80, v114
	v_add_u32_e32 v110, 0x80, v110
	v_mfma_f32_16x16x32_bf16 v[116:119], v[120:123], v[116:119], 0
	v_cvt_pk_bf16_f32 v120, v48, v49
	v_cvt_pk_bf16_f32 v121, v50, v51
	s_cmp_eq_u32 s70, 0x1b90000
	v_add_u32_e32 v111, 0x80, v111
	v_cvt_pk_bf16_f32 v122, v44, v45
	s_nop 5
	v_fma_f32 v76, v124, v59, v116
	v_fma_f32 v115, v125, v59, v117
	v_fma_f32 v116, v126, v59, v118
	v_fmac_f32_e32 v119, v127, v59
	v_mul_f32_e32 v76, v76, v56
	v_mul_f32_e32 v115, v115, v56
	v_mul_f32_e32 v117, v116, v56
	v_mul_f32_e32 v56, v119, v56
	v_mov_b64_e32 v[118:119], s[28:29]
	v_mad_i64_i32 v[118:119], s[72:73], v109, s84, v[118:119]
	v_lshl_add_u64 v[118:119], v[118:119], 0, s[42:43]
	v_lshl_add_u64 v[118:119], v[118:119], 0, s[58:59]
	v_lshl_add_u64 v[118:119], s[56:57], 1, v[118:119]
	v_lshl_add_u64 v[118:119], v[118:119], 0, v[60:61]
	v_add_co_u32_e32 v118, vcc, s85, v118
	v_cvt_pk_bf16_f32 v116, v76, v115
	v_cvt_pk_bf16_f32 v117, v117, v56
	v_add_u32_e32 v59, 0xc000, v113
	s_nop 0
	v_addc_co_u32_e32 v119, vcc, 0, v119, vcc
	global_store_dwordx2 v[118:119], v[116:117], off
	v_cvt_pk_bf16_f32 v116, v36, v37
	v_cvt_pk_bf16_f32 v117, v38, v39
	s_waitcnt lgkmcnt(0)
	s_barrier
	v_cvt_pk_bf16_f32 v126, v32, v33
	v_cvt_pk_bf16_f32 v127, v34, v35
	ds_write2_b64 v59, v[116:117], v[126:127] offset1:2
	v_cvt_pk_bf16_f32 v116, v28, v29
	v_cvt_pk_bf16_f32 v117, v30, v31
	v_add_u32_e32 v76, 0xe000, v113
	v_cvt_pk_bf16_f32 v118, v52, v53
	v_cvt_pk_bf16_f32 v119, v54, v55
	ds_write2_b64 v76, v[118:119], v[116:117] offset0:32 offset1:34
	v_cvt_pk_bf16_f32 v116, v24, v25
	v_cvt_pk_bf16_f32 v117, v26, v27
	ds_write2_b64 v85, v[120:121], v[116:117] offset1:2
	v_cvt_pk_bf16_f32 v116, v20, v21
	v_cvt_pk_bf16_f32 v117, v22, v23
	v_add_u32_e32 v115, 0xe000, v86
	v_add_u32_e32 v109, 32, v109
	v_cvt_pk_bf16_f32 v123, v46, v47
	v_cvt_pk_bf16_f32 v124, v40, v41
	v_cvt_pk_bf16_f32 v125, v42, v43
	ds_write2_b64 v115, v[122:123], v[116:117] offset0:32 offset1:34
	v_cvt_pk_bf16_f32 v116, v16, v17
	v_cvt_pk_bf16_f32 v117, v18, v19
	ds_write2_b64 v67, v[124:125], v[116:117] offset0:32 offset1:34
	s_cbranch_scc1 .LBB0_676

; #define LAS __attribute__((address_space(3)))
; __device__ __forceinline__ unsigned pk2(float lo, float hi) { unsigned r; asm("v_cvt_pk_bf16_f32 %0, %1, %2" : "=v"(r) : "v"(lo), "v"(hi)); return r; }
; __device__ __forceinline__ void mlstm_item(const Args& a, LAS unsigned char* L, bool sample, int b, int hh, int sl, bool dry = false) {
;     ...
;         if (wave < 4) {
;             const int st = wave >> 1, tt = wave & 1, t = tt * 16 + lr;
;             f32x4 s = (f32x4){0.f, 0.f, 0.f, 0.f};
;             if (!(st == 1 && tt == 0)) {
;                 bf16x8 Af[8], Bf[8];
; #pragma unroll
;                 for (int kk = 0; kk < 8; ++kk) { Af[kk] = *(const LAS bf16x8*)(L + L_KS + (st * 16 + lr) * 528 + kk * 64 + g * 16); Bf[kk] = *(const LAS bf16x8*)(L + L_QS + t * 528 + kk * 64 + g * 16); }
;                 __builtin_amdgcn_sched_barrier(0);
; #pragma unroll
;                 for (int kk = 0; kk < 8; ++kk) s = MFMA16(Af[kk], Bf[kk], s);
;             }
;             const float fmt = GFM[c * 32 + t];
;             const f32x4 as4 = *(const LAS f32x4*)(L + L_GAA + (c * 32 + st * 16 + g * 4) * 4);
;             float val[4];
; #pragma unroll
;             for (int j = 0; j < 4; ++j) { const int si = st * 16 + g * 4 + j; const float e = __expf(fminf(fmt + as4[j], 0.f)); val[j] = (si <= t) ? s[j] * e : 0.f; }
;             *(LAS u32x2*)(L + L_SS + t * 80 + (st * 16 + g * 4) * 2) = (u32x2){pk2(val[0], val[1]), pk2(val[2], val[3])};
;             float rsum = (val[0] + val[1]) + (val[2] + val[3]);
;             rsum += __shfl_xor(rsum, 16); rsum += __shfl_xor(rsum, 32);
;             if (g == 0) *(LAS float*)(L + L_NQ + (st * 32 + t) * 4) = rsum;
;         } else {
;             const int w4 = wave - 4, tt = w4 & 1, kh = w4 >> 1, t = tt * 16 + lr;
;             f32x4 cA = (f32x4){0.f, 0.f, 0.f, 0.f};
;             bf16x8 Af[4], Bf[4];
; #pragma unroll
;             for (int kk = 0; kk < 4; ++kk) { const int ko = (kh * 4 + kk) * 64 + g * 16; Af[kk] = *(const LAS bf16x8*)(L + L_CS + (64 + lr) * 528 + ko); Bf[kk] = *(const LAS bf16x8*)(L + L_QS + t * 528 + ko); }
;             __builtin_amdgcn_sched_barrier(0);
; #pragma unroll
;             for (int kk = 0; kk < 4; ++kk) cA = MFMA16(Af[kk], Bf[kk], cA);
;             if (g == 0) *(LAS float*)(L + L_NQ + (64 + kh * 32 + t) * 4) = cA[0];
.LBB0_667:
	s_or_b64 exec, exec, s[72:73]
	s_add_i32 s17, s16, 0
	s_add_i32 s42, s17, 0x1e600
	s_waitcnt lgkmcnt(0)
	s_barrier
	v_mov_b32_e32 v56, s42
	s_add_i32 s17, s17, 0x1e500
	v_mov_b32_e32 v57, s17
	ds_read_b32 v76, v56
	ds_read_b32 v115, v57
	s_mov_b64 s[72:73], -1
	s_and_b64 vcc, exec, s[68:69]
	s_cbranch_vccz .LBB0_671
	v_add_u32_e32 v132, v105, v103
	v_add_u32_e32 v140, v104, v103
	ds_read_b128 v[56:59], v132 offset:33792
	ds_read_b128 v[116:119], v132 offset:33824
	ds_read_b128 v[120:123], v140
	ds_read_b128 v[124:127], v140 offset:32
	ds_read_b128 v[128:131], v132 offset:33856
	ds_read_b128 v[132:135], v132 offset:33888
	ds_read_b128 v[136:139], v140 offset:64
	ds_read_b128 v[140:143], v140 offset:96
	s_waitcnt lgkmcnt(5)
	v_mfma_f32_16x16x32_bf16 v[56:59], v[56:59], v[120:123], 0
	s_waitcnt lgkmcnt(4)
	v_mfma_f32_16x16x32_bf16 v[56:59], v[116:119], v[124:127], v[56:59]
	s_waitcnt lgkmcnt(1)
	v_mfma_f32_16x16x32_bf16 v[56:59], v[128:131], v[136:139], v[56:59]
	s_waitcnt lgkmcnt(0)
	v_mfma_f32_16x16x32_bf16 v[56:59], v[132:135], v[140:143], v[56:59]
	s_and_saveexec_b64 s[72:73], s[4:5]
	s_nop 6
	v_add_u32_e32 v57, 0, v102
	v_add_u32_e32 v57, 0x1e800, v57
	ds_write_b32 v57, v56
	s_or_b64 exec, exec, s[72:73]
	s_mov_b64 s[72:73], 0
.LBB0_671:
	s_andn2_b64 vcc, exec, s[72:73]
	s_cbranch_vccnz .LBB0_661
	v_mov_b32_e32 v56, 0
	s_andn2_b64 vcc, exec, s[64:65]
	v_mov_b32_e32 v57, 0
	v_mov_b32_e32 v58, 0
	v_mov_b32_e32 v59, 0
	s_cbranch_vccnz .LBB0_674
	v_add_u32_e32 v164, v101, v222
	v_add_u32_e32 v172, v100, v222
	ds_read_b128 v[56:59], v164 offset:16896
	ds_read_b128 v[116:119], v164 offset:16928
	ds_read_b128 v[120:123], v172
	ds_read_b128 v[124:127], v172 offset:32
	ds_read_b128 v[128:131], v164 offset:16960
	ds_read_b128 v[132:135], v164 offset:16992
	ds_read_b128 v[136:139], v172 offset:64
	ds_read_b128 v[140:143], v172 offset:96
	ds_read_b128 v[144:147], v164 offset:17024
	ds_read_b128 v[148:151], v164 offset:17056
	ds_read_b128 v[152:155], v172 offset:128
	ds_read_b128 v[156:159], v172 offset:160
	ds_read_b128 v[160:163], v164 offset:17088
	ds_read_b128 v[164:167], v164 offset:17120
	ds_read_b128 v[168:171], v172 offset:192
	ds_read_b128 v[172:175], v172 offset:224
	s_waitcnt lgkmcnt(13)
	v_mfma_f32_16x16x32_bf16 v[56:59], v[56:59], v[120:123], 0
	s_waitcnt lgkmcnt(12)
	v_mfma_f32_16x16x32_bf16 v[56:59], v[116:119], v[124:127], v[56:59]
	s_waitcnt lgkmcnt(9)
	v_mfma_f32_16x16x32_bf16 v[56:59], v[128:131], v[136:139], v[56:59]
	s_waitcnt lgkmcnt(8)
	v_mfma_f32_16x16x32_bf16 v[56:59], v[132:135], v[140:143], v[56:59]
	s_waitcnt lgkmcnt(5)
	v_mfma_f32_16x16x32_bf16 v[56:59], v[144:147], v[152:155], v[56:59]
	s_waitcnt lgkmcnt(4)
	v_mfma_f32_16x16x32_bf16 v[56:59], v[148:151], v[156:159], v[56:59]
	s_waitcnt lgkmcnt(1)
	v_mfma_f32_16x16x32_bf16 v[56:59], v[160:163], v[168:171], v[56:59]
	s_waitcnt lgkmcnt(0)
	v_mfma_f32_16x16x32_bf16 v[56:59], v[164:167], v[172:175], v[56:59]

; #define LAS __attribute__((address_space(3)))
; __device__ __forceinline__ unsigned pk2(float lo, float hi) { unsigned r; asm("v_cvt_pk_bf16_f32 %0, %1, %2" : "=v"(r) : "v"(lo), "v"(hi)); return r; }
; __device__ __forceinline__ void mlstm_item(const Args& a, LAS unsigned char* L, bool sample, int b, int hh, int sl, bool dry = false) {
;     ...
;         if (wave < 4) {
;             const int st = wave >> 1, tt = wave & 1, t = tt * 16 + lr;
;             f32x4 s = (f32x4){0.f, 0.f, 0.f, 0.f};
;             if (!(st == 1 && tt == 0)) {
;                 bf16x8 Af[8], Bf[8];
; #pragma unroll
;                 for (int kk = 0; kk < 8; ++kk) { Af[kk] = *(const LAS bf16x8*)(L + L_KS + (st * 16 + lr) * 528 + kk * 64 + g * 16); Bf[kk] = *(const LAS bf16x8*)(L + L_QS + t * 528 + kk * 64 + g * 16); }
;                 __builtin_amdgcn_sched_barrier(0);
; #pragma unroll
;                 for (int kk = 0; kk < 8; ++kk) s = MFMA16(Af[kk], Bf[kk], s);
;             }
;             const float fmt = GFM[c * 32 + t];
;             const f32x4 as4 = *(const LAS f32x4*)(L + L_GAA + (c * 32 + st * 16 + g * 4) * 4);
;             float val[4];
; #pragma unroll
;             for (int j = 0; j < 4; ++j) { const int si = st * 16 + g * 4 + j; const float e = __expf(fminf(fmt + as4[j], 0.f)); val[j] = (si <= t) ? s[j] * e : 0.f; }
;             *(LAS u32x2*)(L + L_SS + t * 80 + (st * 16 + g * 4) * 2) = (u32x2){pk2(val[0], val[1]), pk2(val[2], val[3])};
;             float rsum = (val[0] + val[1]) + (val[2] + val[3]);
;             rsum += __shfl_xor(rsum, 16); rsum += __shfl_xor(rsum, 32);
;             if (g == 0) *(LAS float*)(L + L_NQ + (st * 32 + t) * 4) = rsum;
;         } else {
;             const int w4 = wave - 4, tt = w4 & 1, kh = w4 >> 1, t = tt * 16 + lr;
;             f32x4 cA = (f32x4){0.f, 0.f, 0.f, 0.f};
;             bf16x8 Af[4], Bf[4];
; #pragma unroll
;             for (int kk = 0; kk < 4; ++kk) { const int ko = (kh * 4 + kk) * 64 + g * 16; Af[kk] = *(const LAS bf16x8*)(L + L_CS + (64 + lr) * 528 + ko); Bf[kk] = *(const LAS bf16x8*)(L + L_QS + t * 528 + ko); }
;             __builtin_amdgcn_sched_barrier(0);
; #pragma unroll
;             for (int kk = 0; kk < 4; ++kk) cA = MFMA16(Af[kk], Bf[kk], cA);
;             if (g == 0) *(LAS float*)(L + L_NQ + (64 + kh * 32 + t) * 4) = cA[0];
.LBB0_679:
	s_or_b64 exec, exec, s[70:71]
	s_waitcnt lgkmcnt(0)
	s_barrier
	v_mov_b32_e32 v0, s89
	v_mov_b32_e32 v1, s90
	ds_read_b32 v56, v0
	ds_read_b32 v62, v1
	s_andn2_b64 vcc, exec, s[68:69]
	s_mov_b64 s[0:1], -1
	s_cbranch_vccnz .LBB0_683
	v_add_u32_e32 v63, v105, v103
	v_add_u32_e32 v64, v104, v103
	ds_read_b128 v[0:3], v63 offset:33792
	ds_read_b128 v[4:7], v63 offset:33824
	ds_read_b128 v[8:11], v64
	ds_read_b128 v[12:15], v64 offset:32
	ds_read_b128 v[72:75], v63 offset:33856
	ds_read_b128 v[104:107], v63 offset:33888
	ds_read_b128 v[108:111], v64 offset:64
	ds_read_b128 v[116:119], v64 offset:96
	s_waitcnt lgkmcnt(5)
	v_mfma_f32_16x16x32_bf16 v[0:3], v[0:3], v[8:11], 0
	s_waitcnt lgkmcnt(4)
	v_mfma_f32_16x16x32_bf16 v[0:3], v[4:7], v[12:15], v[0:3]
	s_waitcnt lgkmcnt(1)
	v_mfma_f32_16x16x32_bf16 v[0:3], v[72:75], v[108:111], v[0:3]
	s_waitcnt lgkmcnt(0)
	v_mfma_f32_16x16x32_bf16 v[0:3], v[104:107], v[116:119], v[0:3]
	s_and_saveexec_b64 s[0:1], s[4:5]
	s_nop 6
	v_add_u32_e32 v1, 0, v102
	v_add_u32_e32 v1, 0x1e800, v1
	ds_write_b32 v1, v0
	s_or_b64 exec, exec, s[0:1]
	s_mov_b64 s[0:1], 0
.LBB0_683:
	s_andn2_b64 vcc, exec, s[0:1]
	s_cbranch_vccnz .LBB0_689
	v_mov_b32_e32 v0, 0
	s_andn2_b64 vcc, exec, s[64:65]
	v_mov_b32_e32 v1, 0
	v_mov_b32_e32 v2, 0
	v_mov_b32_e32 v3, 0
	s_cbranch_vccnz .LBB0_686
	v_add_u32_e32 v63, v101, v222
	v_add_u32_e32 v64, v100, v222
	ds_read_b128 v[0:3], v63 offset:16896
	ds_read_b128 v[4:7], v63 offset:16928
	ds_read_b128 v[8:11], v64
	ds_read_b128 v[12:15], v64 offset:32
	ds_read_b128 v[72:75], v63 offset:16960
	ds_read_b128 v[100:103], v63 offset:16992
	ds_read_b128 v[104:107], v64 offset:64
	ds_read_b128 v[108:111], v64 offset:96
	ds_read_b128 v[116:119], v63 offset:17024
	ds_read_b128 v[120:123], v63 offset:17056
	ds_read_b128 v[124:127], v64 offset:128
	ds_read_b128 v[128:131], v64 offset:160
	ds_read_b128 v[132:135], v63 offset:17088
	ds_read_b128 v[136:139], v63 offset:17120
	ds_read_b128 v[140:143], v64 offset:192
	ds_read_b128 v[144:147], v64 offset:224
	s_waitcnt lgkmcnt(13)
	v_mfma_f32_16x16x32_bf16 v[0:3], v[0:3], v[8:11], 0
	s_waitcnt lgkmcnt(12)
	v_mfma_f32_16x16x32_bf16 v[0:3], v[4:7], v[12:15], v[0:3]
	s_waitcnt lgkmcnt(9)
	v_mfma_f32_16x16x32_bf16 v[0:3], v[72:75], v[104:107], v[0:3]
	s_waitcnt lgkmcnt(8)
	v_mfma_f32_16x16x32_bf16 v[0:3], v[100:103], v[108:111], v[0:3]
	s_waitcnt lgkmcnt(5)
	v_mfma_f32_16x16x32_bf16 v[0:3], v[116:119], v[124:127], v[0:3]
	s_waitcnt lgkmcnt(4)
	v_mfma_f32_16x16x32_bf16 v[0:3], v[120:123], v[128:131], v[0:3]
	s_waitcnt lgkmcnt(1)
	v_mfma_f32_16x16x32_bf16 v[0:3], v[132:135], v[140:143], v[0:3]
	s_waitcnt lgkmcnt(0)
	v_mfma_f32_16x16x32_bf16 v[0:3], v[136:139], v[144:147], v[0:3]

; #define LAS __attribute__((address_space(3)))
; __device__ __forceinline__ void mlstm_item(const Args& a, LAS unsigned char* L, bool sample, int b, int hh, int sl, bool dry = false) {
;     ...
;             v4i16_t tl[2], th[2]; bf16x8 Bv[5];
; #pragma unroll
;             for (int kti = 0; kti < 2; ++kti) { const int kt = 2 * wave + kti;
;                 tl[kti] = __builtin_amdgcn_ds_read_tr16_b64_v4i16((LAS v4i16_t*)(L + L_KS + (g * 8 + (lr >> 2)) * 528 + (kt * 16 + 4 * (lr & 3)) * 2));
;                 th[kti] = __builtin_amdgcn_ds_read_tr16_b64_v4i16((LAS v4i16_t*)(L + L_KS + (g * 8 + 4 + (lr >> 2)) * 528 + (kt * 16 + 4 * (lr & 3)) * 2)); }
; #pragma unroll
;             for (int vt = 0; vt < 5; ++vt) Bv[vt] = *(const LAS bf16x8*)(L + L_VTW + (vt * 16 + lr) * 80 + g * 16);
; #pragma unroll
;             for (int kti = 0; kti < 2; ++kti) { const bf16x8 A = (bf16x8){tl[kti][0], tl[kti][1], tl[kti][2], tl[kti][3], th[kti][0], th[kti][1], th[kti][2], th[kti][3]};
; #pragma unroll
;                 for (int vt = 0; vt < 5; ++vt) Cacc[kti][vt] = MFMA16(A, Bv[vt], Cacc[kti][vt] * dL); }
;         }
;         LDS_BARRIER();
;         {
;             const int tt = wave & 1, vt = wave >> 1, t = tt * 16 + lr;
;             const bf16x8 Bs = *(const LAS bf16x8*)(L + L_SS + t * 80 + g * 16);
;             const f32x4 z4 = (f32x4){0.f, 0.f, 0.f, 0.f};
;             const bf16x8 Av = *(const LAS bf16x8*)(L + L_VT + (vt * 16 + lr) * 80 + g * 16);
;             bf16x8 Af[8], Bf[8];
; #pragma unroll
;             for (int kk = 0; kk < 8; ++kk) { Af[kk] = *(const LAS bf16x8*)(L + L_CS + (vt * 16 + lr) * 528 + kk * 64 + g * 16); Bf[kk] = *(const LAS bf16x8*)(L + L_QS + t * 528 + kk * 64 + g * 16); }
;             __builtin_amdgcn_sched_barrier(0);
;             f32x4 sM = MFMA16(Av, Bs, z4);
;             f32x4 cM = z4;
; #pragma unroll
;             for (int kk = 0; kk < 8; ++kk) cM = MFMA16(Af[kk], Bf[kk], cM);
;             const float d0 = __expf(m0c + GFM[c * 32 + t]), en = GEN[c * 32 + t];
;             const LAS float* NQ = (const LAS float*)(L + L_NQ);
;             const float nq = (NQ[t] + NQ[32 + t]) + d0 * (NQ[64 + t] + NQ[96 + t]);
;             const float inv = __builtin_amdgcn_rcpf(fmaxf(fabsf(nq), en));
;             float hv[4];
; #pragma unroll
;             for (int j = 0; j < 4; ++j) hv[j] = (sM[j] + d0 * cM[j]) * inv;
.LBB0_689:
	ds_read_b64_tr_b16 v[2:3], v97 offset:19008
	s_waitcnt lgkmcnt(1)
	ds_read_b64_tr_b16 v[0:1], v97 offset:16896
	ds_read_b128 v[4:7], v95 offset:40192
	ds_read_b64_tr_b16 v[74:75], v97 offset:19024
	ds_read_b64_tr_b16 v[72:73], v97 offset:16912
	ds_read_b128 v[8:11], v95 offset:41472
	v_pk_mul_f32 v[14:15], v[38:39], v[56:57] op_sel_hi:[1,0]
	v_pk_mul_f32 v[12:13], v[36:37], v[56:57] op_sel_hi:[1,0]
	ds_read_b128 v[96:99], v95 offset:42752
	v_pk_mul_f32 v[38:39], v[54:55], v[56:57] op_sel_hi:[1,0]
	v_pk_mul_f32 v[36:37], v[52:53], v[56:57] op_sel_hi:[1,0]
	ds_read_b128 v[52:55], v95 offset:44032
	ds_read_b128 v[92:95], v95 offset:45312
	v_pk_mul_f32 v[50:51], v[50:51], v[56:57] op_sel_hi:[1,0]
	v_pk_mul_f32 v[48:49], v[48:49], v[56:57] op_sel_hi:[1,0]
	v_pk_mul_f32 v[46:47], v[46:47], v[56:57] op_sel_hi:[1,0]
	v_pk_mul_f32 v[44:45], v[44:45], v[56:57] op_sel_hi:[1,0]
	v_pk_mul_f32 v[42:43], v[42:43], v[56:57] op_sel_hi:[1,0]
	v_pk_mul_f32 v[40:41], v[40:41], v[56:57] op_sel_hi:[1,0]
	s_waitcnt lgkmcnt(6)
	v_mfma_f32_16x16x32_bf16 v[12:15], v[0:3], v[4:7], v[12:15]
	v_mul_f32_e64 v22, v22, v56
	v_mul_f32_e64 v23, v23, v56
	v_pk_mul_f32 v[20:21], v[20:21], v[56:57] op_sel_hi:[1,0]
	s_waitcnt lgkmcnt(0)
	s_waitcnt lgkmcnt(3)
	v_mfma_f32_16x16x32_bf16 v[36:39], v[0:3], v[8:11], v[36:39]
	s_barrier
	v_pk_mul_f32 v[18:19], v[18:19], v[56:57] op_sel_hi:[1,0]
	s_waitcnt lgkmcnt(2)
	v_mfma_f32_16x16x32_bf16 v[48:51], v[0:3], v[96:99], v[48:51]
	v_mul_f32_e64 v16, v16, v56
	v_mul_f32_e64 v17, v17, v56
	s_waitcnt lgkmcnt(1)
	v_mfma_f32_16x16x32_bf16 v[44:47], v[0:3], v[52:55], v[44:47]
	s_waitcnt lgkmcnt(0)
	v_mfma_f32_16x16x32_bf16 v[40:43], v[0:3], v[92:95], v[40:43]
	v_mul_f32_e64 v2, v34, v56
	v_mul_f32_e64 v3, v35, v56
	v_pk_mul_f32 v[0:1], v[32:33], v[56:57] op_sel_hi:[1,0]
	v_mfma_f32_16x16x32_bf16 v[20:23], v[72:75], v[52:55], v[20:23]
	s_nop 0
	v_mfma_f32_16x16x32_bf16 v[0:3], v[72:75], v[4:7], v[0:3]
	v_mul_f32_e64 v6, v30, v56
	v_mul_f32_e64 v7, v31, v56
	v_pk_mul_f32 v[4:5], v[28:29], v[56:57] op_sel_hi:[1,0]
	v_mfma_f32_16x16x32_bf16 v[16:19], v[72:75], v[92:95], v[16:19]
	s_nop 0
	v_mfma_f32_16x16x32_bf16 v[4:7], v[72:75], v[8:11], v[4:7]
	v_mul_f32_e64 v10, v26, v56
	v_mul_f32_e64 v11, v27, v56
	v_pk_mul_f32 v[8:9], v[24:25], v[56:57] op_sel_hi:[1,0]
	s_nop 1
	v_mfma_f32_16x16x32_bf16 v[8:11], v[72:75], v[96:99], v[8:11]
	ds_read_b128 v[24:27], v91 offset:46592
	ds_read_b128 v[28:31], v58 offset:33792
	ds_read_b128 v[32:35], v90 offset:49152
	ds_read_b128 v[52:55], v90 offset:49184
	ds_read_b128 v[96:99], v57
	ds_read_b128 v[100:103], v57 offset:32
	ds_read_b128 v[104:107], v90 offset:49216
	ds_read_b128 v[108:111], v90 offset:49248
	ds_read_b128 v[116:119], v57 offset:64
	ds_read_b128 v[120:123], v57 offset:96
	ds_read_b128 v[124:127], v90 offset:49280
	ds_read_b128 v[128:131], v90 offset:49312
	ds_read_b128 v[132:135], v57 offset:128
	ds_read_b128 v[136:139], v57 offset:160
	ds_read_b128 v[140:143], v90 offset:49344
	ds_read_b128 v[144:147], v90 offset:49376
	ds_read_b128 v[148:151], v57 offset:192
	ds_read_b128 v[152:155], v57 offset:224
	s_waitcnt lgkmcnt(13)
	v_mfma_f32_16x16x32_bf16 v[32:35], v[32:35], v[96:99], 0
	v_or_b32_e32 v58, 0x7e0, v88
	s_mov_b32 s59, s43
	s_ashr_i32 s53, s52, 31
	s_waitcnt lgkmcnt(12)
	v_mfma_f32_16x16x32_bf16 v[32:35], v[52:55], v[100:103], v[32:35]
	v_lshl_add_u32 v52, v58, 2, 0
	v_add_u32_e32 v53, 0x16500, v52
	ds_read_b32 v56, v53
	s_waitcnt lgkmcnt(10)
	v_mfma_f32_16x16x32_bf16 v[32:35], v[104:107], v[116:119], v[32:35]
	v_add_u32_e32 v54, 0x1a500, v52
	ds_read2_b32 v[52:53], v89 offset1:32
	ds_read_b32 v63, v54
	ds_read2_b32 v[54:55], v89 offset0:64 offset1:96
	s_waitcnt lgkmcnt(12)
	v_mfma_f32_16x16x32_bf16 v[32:35], v[108:111], v[120:123], v[32:35]
	s_waitcnt lgkmcnt(3)
	v_add_f32_e32 v56, v62, v56
	v_mul_f32_e32 v62, 0x3fb8aa3b, v56
	v_exp_f32_e32 v62, v62
	v_mfma_f32_16x16x32_bf16 v[32:35], v[124:127], v[132:135], v[32:35]
	s_waitcnt lgkmcnt(2)
	v_mov_b32_e32 v56, v52
	s_waitcnt lgkmcnt(0)
	v_mov_b32_e32 v57, v54
	v_mov_b32_e32 v54, v53
	v_mfma_f32_16x16x32_bf16 v[32:35], v[128:131], v[136:139], v[32:35]
	v_add_f32_e64 v52, v56, v54
	v_add_f32_e64 v53, v57, v55
	v_fmac_f32_e32 v52, v62, v53
	v_mfma_f32_16x16x32_bf16 v[32:35], v[140:143], v[148:151], v[32:35]
	v_max_f32_e32 v53, v63, v63
	v_max_f32_e64 v52, |v52|, v53
	v_rcp_f32_e32 v52, v52
	v_mfma_f32_16x16x32_bf16 v[32:35], v[144:147], v[152:155], v[32:35]
	v_mfma_f32_16x16x32_bf16 v[24:27], v[28:31], v[24:27], 0
	v_or_b32_e32 v28, s54, v58
	v_cvt_pk_bf16_f32 v29, v50, v51
	v_cvt_pk_bf16_f32 v30, v44, v45
	v_cvt_pk_bf16_f32 v31, v46, v47
	s_nop 6
	v_fma_f32 v24, v32, v62, v24
	v_fma_f32 v25, v33, v62, v25
	v_fma_f32 v26, v34, v62, v26
	v_fmac_f32_e32 v27, v35, v62
	v_mul_f32_e32 v24, v24, v52
	v_mul_f32_e32 v25, v25, v52
	v_mul_f32_e32 v26, v26, v52
	v_mul_f32_e32 v27, v27, v52
	v_cvt_pk_bf16_f32 v24, v24, v25
	v_cvt_pk_bf16_f32 v25, v26, v27
	v_mov_b64_e32 v[26:27], s[28:29]
	v_mad_i64_i32 v[26:27], s[0:1], v28, s84, v[26:27]
	v_lshl_add_u64 v[26:27], v[26:27], 0, s[42:43]
	v_lshl_add_u64 v[26:27], v[26:27], 0, s[58:59]
	v_lshl_add_u64 v[26:27], s[56:57], 1, v[26:27]
	v_lshl_add_u64 v[26:27], v[26:27], 0, v[60:61]
	v_add_co_u32_e32 v26, vcc, s85, v26
	v_cvt_pk_bf16_f32 v34, v0, v1
	v_cvt_pk_bf16_f32 v35, v2, v3
	s_lshl_b64 s[0:1], s[52:53], 18
	s_nop 0
	v_addc_co_u32_e32 v27, vcc, 0, v27, vcc
	global_store_dwordx2 v[26:27], v[24:25], off
	v_cvt_pk_bf16_f32 v24, v12, v13
	v_cvt_pk_bf16_f32 v25, v14, v15
	s_waitcnt lgkmcnt(0)
	s_barrier
; #define WRITE_CS() do { _Pragma("unroll") for (int kti = 0; kti < 2; ++kti) _Pragma("unroll") for (int vt = 0; vt < 5; ++vt) \
;         *(LAS u32x2*)(L + L_CS + (vt * 16 + lr) * 528 + ((2 * wave + kti) * 16 + g * 4) * 2) = (u32x2){pk2(Cacc[kti][vt][0], Cacc[kti][vt][1]), pk2(Cacc[kti][vt][2], Cacc[kti][vt][3])}; } while (0)
; __device__ __forceinline__ void mlstm_item(const Args& a, LAS unsigned char* L, bool sample, int b, int hh, int sl, bool dry = false) {
;     ...
;         WRITE_CS();
;     }
;     {
;         float* oC = a.out + (sample ? O_CS : O_CP) + (size_t)(b * 4 + hh) * 65536;
; #pragma unroll
;         for (int kti = 0; kti < 2; ++kti)
; #pragma unroll
;             for (int j = 0; j < 4; ++j) { const int k = (2 * wave + kti) * 16 + g * 4 + j;
; #pragma unroll
;                 for (int vt = 0; vt < 4; ++vt) oC[(size_t)k * 256 + sl * 64 + vt * 16 + lr] = Cacc[kti][vt][j];
;                 if (sl == 0 && lr == 0) a.out[(sample ? O_NS : O_NP) + (size_t)(b * 4 + hh) * 256 + k] = Cacc[kti][4][j]; }
	ds_write2_b64 v59, v[24:25], v[34:35] offset1:2
	v_cvt_pk_bf16_f32 v24, v4, v5
	v_cvt_pk_bf16_f32 v25, v6, v7
	v_cvt_pk_bf16_f32 v26, v36, v37
	v_cvt_pk_bf16_f32 v27, v38, v39
	ds_write2_b64 v76, v[26:27], v[24:25] offset0:32 offset1:34
	v_cvt_pk_bf16_f32 v24, v8, v9
	v_cvt_pk_bf16_f32 v25, v10, v11
	s_add_u32 s0, s76, s0
	v_cvt_pk_bf16_f32 v28, v48, v49
	ds_write2_b64 v85, v[28:29], v[24:25] offset1:2
	v_cvt_pk_bf16_f32 v24, v20, v21
	v_cvt_pk_bf16_f32 v25, v22, v23
	s_addc_u32 s1, s77, s1
	s_lshl_b32 s4, s97, 2
	ds_write2_b64 v115, v[30:31], v[24:25] offset0:32 offset1:34
	v_cvt_pk_bf16_f32 v24, v16, v17
	v_cvt_pk_bf16_f32 v25, v18, v19
	s_add_u32 s0, s0, s4
	v_cvt_pk_bf16_f32 v32, v40, v41
	v_cvt_pk_bf16_f32 v33, v42, v43
	ds_write2_b64 v67, v[32:33], v[24:25] offset0:32 offset1:34
	v_lshl_or_b32 v24, s55, 5, v68
	s_addc_u32 s1, s1, 0
	v_mov_b32_e32 v67, v61
	v_or_b32_e32 v25, s94, v84
	v_lshl_add_u64 v[26:27], s[0:1], 0, v[66:67]
	v_cmp_eq_u32_e32 vcc, 0, v25
	s_lshl_b64 s[0:1], s[52:53], 10
	v_ashrrev_i32_e32 v25, 31, v24
	s_add_u32 s0, s78, s0
	v_lshlrev_b64 v[28:29], 10, v[24:25]
	s_addc_u32 s1, s79, s1
	v_lshl_add_u64 v[28:29], v[26:27], 0, v[28:29]
	global_store_dword v[28:29], v12, off
	global_store_dword v[28:29], v36, off offset:64
	global_store_dword v[28:29], v48, off offset:128
	global_store_dword v[28:29], v44, off offset:192
	v_lshl_add_u64 v[28:29], v[24:25], 2, s[0:1]
	s_and_saveexec_b64 s[0:1], vcc
	s_cbranch_execz .LBB0_691
	global_store_dword v[28:29], v40, off
